# part of the softmax exps (14 of 64 in the MLA loop, 6 in the GQA loop) issued early inside QK MFMA gaps; rare rescale path multiplies them by alpha
# speedup vs baseline: 1.0085x; 1.0047x over previous
.Lmla_B_ls_end:
	s_add_i32 s6, s14, -4
	s_and_b32 s6, s6, 2
	s_mul_i32 s7, s6, 0x2400
	v_add_f32_e32 v201, v91, v201
	v_add_f32_e32 v247, v92, v247
	v_add_f32_e32 v201, v93, v201
	v_add_f32_e32 v247, v94, v247
	v_add_f32_e32 v201, v95, v201
	v_add_f32_e32 v247, v96, v247
	s_waitcnt lgkmcnt(6)
	v_mfma_f32_32x32x16_bf16 v[50:65], v[238:241], v[126:129], v[50:65]
	ds_read_b128 v[238:241], v0 offset:6784
	v_add_f32_e32 v201, v97, v201
	v_add_f32_e32 v247, v98, v247
	v_add_f32_e32 v201, v99, v201
	v_add_f32_e32 v247, v100, v247
	v_add_f32_e32 v201, v101, v201
	v_add_f32_e32 v247, v102, v247
	s_waitcnt lgkmcnt(6)
	v_mfma_f32_32x32x16_bf16 v[50:65], v[242:245], v[130:133], v[50:65]
	ds_read_b128 v[242:245], v0 offset:6816
	v_add_f32_e32 v201, v103, v201
	v_add_f32_e32 v247, v104, v247
	v_add_f32_e32 v201, v105, v201
	v_add_f32_e32 v247, v106, v247
	v_add_f32_e32 v201, v107, v201
	v_add_f32_e32 v247, v108, v247
	s_waitcnt lgkmcnt(6)
	v_mfma_f32_32x32x16_bf16 v[50:65], v[162:165], v[134:137], v[50:65]
	ds_read_b128 v[162:165], v225
	v_add_f32_e32 v201, v109, v201
	v_add_f32_e32 v247, v110, v247
	v_add_f32_e32 v201, v111, v201
	v_add_f32_e32 v247, v112, v247
	v_add_f32_e32 v201, v113, v201
	v_add_f32_e32 v247, v246, v247
	s_waitcnt lgkmcnt(6)
	v_mfma_f32_32x32x16_bf16 v[66:81], v[166:169], v[114:117], v[34:49]
	ds_read_b128 v[166:169], v225 offset:32
	v_add_f32_e32 v201, v202, v201
	v_add_f32_e32 v247, v203, v247
	v_add_f32_e32 v201, v204, v201
	v_add_f32_e32 v247, v205, v247
	s_waitcnt lgkmcnt(6)
	v_mfma_f32_32x32x16_bf16 v[66:81], v[226:229], v[118:121], v[66:81]
	ds_read_b128 v[226:229], v225 offset:64
	v_add_f32_e32 v201, v206, v201
	v_add_f32_e32 v247, v207, v247
	v_add_f32_e32 v201, v208, v201
	v_add_f32_e32 v247, v209, v247
	s_waitcnt lgkmcnt(6)
	v_mfma_f32_32x32x16_bf16 v[66:81], v[230:233], v[122:125], v[66:81]
	ds_read_b128 v[230:233], v225 offset:96
	v_add_f32_e32 v201, v210, v201
	v_add_f32_e32 v247, v211, v247
	v_add_f32_e32 v201, v212, v201
	v_add_f32_e32 v247, v213, v247
	v_max3_f32 v0, v50, v51, v52
	v_max3_f32 v0, v0, v53, v54
	s_waitcnt lgkmcnt(6)
	v_mfma_f32_32x32x16_bf16 v[66:81], v[234:237], v[126:129], v[66:81]
	ds_read_b128 v[234:237], v225 offset:128
	v_add_f32_e32 v201, v214, v201
	v_add_f32_e32 v247, v215, v247
	v_add_f32_e32 v201, v216, v201
	v_add_f32_e32 v247, v217, v247
	v_max3_f32 v0, v0, v55, v56
	v_max3_f32 v0, v0, v57, v58
	s_waitcnt lgkmcnt(6)
	v_mfma_f32_32x32x16_bf16 v[66:81], v[238:241], v[130:133], v[66:81]
	ds_read_b128 v[238:241], v225 offset:160
	v_add_f32_e32 v201, v218, v201
	v_add_f32_e32 v247, v219, v247
	v_add_f32_e32 v201, v220, v201
	v_add_f32_e32 v247, v221, v247
	v_max3_f32 v0, v0, v59, v60
	v_max3_f32 v0, v0, v61, v62
	s_waitcnt lgkmcnt(6)
	v_mfma_f32_32x32x16_bf16 v[66:81], v[242:245], v[134:137], v[66:81]
	ds_read_b128 v[242:245], v225 offset:6656
	v_add_f32_e32 v201, v222, v201
	v_add_f32_e32 v247, v223, v247
	v_add_f32_e32 v201, v224, v201
	v_add_f32_e32 v201, v247, v201
	v_max3_f32 v0, v0, v63, v64
	v_max3_f32 v0, v0, v65, v65
	s_waitcnt lgkmcnt(6)
	v_mfma_f32_32x32x16_bf16 v[82:97], v[162:165], v[114:117], v[34:49]
	ds_read_b128 v[162:165], v225 offset:6688
	v_exp_f32_e32 v246, v50
	v_exp_f32_e32 v202, v51
	s_waitcnt lgkmcnt(6)
	v_mfma_f32_32x32x16_bf16 v[82:97], v[166:169], v[118:121], v[82:97]
	ds_read_b128 v[166:169], v225 offset:6720
	v_add3_u32 v247, v198, s7, v200
	v_exp_f32_e32 v203, v52
	v_exp_f32_e32 v204, v53
	s_waitcnt lgkmcnt(6)
	v_mfma_f32_32x32x16_bf16 v[82:97], v[226:229], v[122:125], v[82:97]
	ds_read_b128 v[226:229], v225 offset:6752
	v_max3_f32 v0, v0, v66, v67
	v_max3_f32 v0, v0, v68, v69
	v_exp_f32_e32 v205, v54
	v_exp_f32_e32 v206, v55
	s_waitcnt lgkmcnt(6)
	v_mfma_f32_32x32x16_bf16 v[82:97], v[230:233], v[126:129], v[82:97]
	ds_read_b128 v[230:233], v225 offset:6784
	v_max3_f32 v0, v0, v70, v71
	v_max3_f32 v0, v0, v72, v73
	v_exp_f32_e32 v207, v56
	v_exp_f32_e32 v208, v57
	s_waitcnt lgkmcnt(6)
	v_mfma_f32_32x32x16_bf16 v[82:97], v[234:237], v[130:133], v[82:97]
	ds_read_b128 v[234:237], v225 offset:6816
	v_max3_f32 v0, v0, v74, v75
	v_max3_f32 v0, v0, v76, v77
	v_exp_f32_e32 v211, v60
	v_exp_f32_e32 v212, v61
	s_waitcnt lgkmcnt(6)
	v_mfma_f32_32x32x16_bf16 v[82:97], v[238:241], v[134:137], v[82:97]
	ds_read_b128 v[238:241], v247 offset:53248
	v_max3_f32 v0, v0, v78, v79
	v_max3_f32 v0, v0, v80, v81
	v_exp_f32_e32 v213, v62
	v_exp_f32_e32 v214, v63
	s_waitcnt lgkmcnt(6)
	v_mfma_f32_32x32x16_bf16 v[98:113], v[242:245], v[114:117], v[34:49]
	ds_read_b128 v[242:245], v247 offset:57856
	v_exp_f32_e32 v215, v64
	v_exp_f32_e32 v216, v65
	s_waitcnt lgkmcnt(6)
	v_mfma_f32_32x32x16_bf16 v[98:113], v[162:165], v[118:121], v[98:113]
	s_waitcnt lgkmcnt(5)
	v_mfma_f32_32x32x16_bf16 v[98:113], v[166:169], v[122:125], v[98:113]
	s_waitcnt lgkmcnt(4)
	v_mfma_f32_32x32x16_bf16 v[98:113], v[226:229], v[126:129], v[98:113]
	ds_read_b128 v[226:229], v247 offset:53280
	s_waitcnt lgkmcnt(4)
	v_mfma_f32_32x32x16_bf16 v[98:113], v[230:233], v[130:133], v[98:113]
	ds_read_b128 v[230:233], v247 offset:57888
	s_waitcnt lgkmcnt(4)
	v_mfma_f32_32x32x16_bf16 v[98:113], v[234:237], v[134:137], v[98:113]
	ds_read_b128 v[234:237], v247 offset:53312
	v_max3_f32 v0, v0, v82, v83
	v_max3_f32 v0, v0, v84, v85
	v_max3_f32 v0, v0, v86, v87
	v_max3_f32 v0, v0, v88, v89
	v_max3_f32 v0, v0, v90, v91
	v_max3_f32 v0, v0, v92, v93
	v_max3_f32 v0, v0, v94, v95
	v_max3_f32 v0, v0, v96, v97
	s_nop 4
	v_max3_f32 v0, v0, v98, v99
	v_max3_f32 v0, v0, v100, v101
	v_max3_f32 v0, v0, v102, v103
	v_max3_f32 v0, v0, v104, v105
	v_max3_f32 v0, v0, v106, v107
	v_max3_f32 v0, v0, v108, v109
	v_max3_f32 v0, v0, v110, v111
	v_max3_f32 v0, v0, v112, v113
	v_mov_b32_e32 v162, v0
	s_nop 1
	v_permlane32_swap_b32_e32 v0, v162
	v_max_f32_e32 v0, v0, v162
	v_cmp_lt_f32_e32 vcc, s50, v0
	s_cbranch_vccz .LBB0_302
	v_max_f32_e32 v0, v0, v0
	v_max_f32_e32 v0, 0, v0
	v_exp_f32_e64 v162, -v0
	v_pk_add_f32 v[50:51], v[50:51], v[0:1] op_sel_hi:[1,0] neg_lo:[0,1] neg_hi:[0,1]
	v_pk_add_f32 v[66:67], v[66:67], v[0:1] op_sel_hi:[1,0] neg_lo:[0,1] neg_hi:[0,1]
	v_pk_add_f32 v[82:83], v[82:83], v[0:1] op_sel_hi:[1,0] neg_lo:[0,1] neg_hi:[0,1]
	v_mul_f32_e32 v201, v201, v162
	v_pk_mul_f32 v[16:17], v[16:17], v[162:163] op_sel_hi:[1,0]
	v_pk_mul_f32 v[14:15], v[14:15], v[162:163] op_sel_hi:[1,0]
	v_pk_mul_f32 v[12:13], v[12:13], v[162:163] op_sel_hi:[1,0]
	v_pk_mul_f32 v[10:11], v[10:11], v[162:163] op_sel_hi:[1,0]
	v_pk_mul_f32 v[8:9], v[8:9], v[162:163] op_sel_hi:[1,0]
	v_pk_mul_f32 v[6:7], v[6:7], v[162:163] op_sel_hi:[1,0]
	v_pk_mul_f32 v[4:5], v[4:5], v[162:163] op_sel_hi:[1,0]
	v_pk_mul_f32 v[2:3], v[2:3], v[162:163] op_sel_hi:[1,0]
	v_pk_mul_f32 v[32:33], v[32:33], v[162:163] op_sel_hi:[1,0]
	v_pk_mul_f32 v[30:31], v[30:31], v[162:163] op_sel_hi:[1,0]
	v_pk_mul_f32 v[28:29], v[28:29], v[162:163] op_sel_hi:[1,0]
	v_pk_mul_f32 v[26:27], v[26:27], v[162:163] op_sel_hi:[1,0]
	v_pk_mul_f32 v[24:25], v[24:25], v[162:163] op_sel_hi:[1,0]
	v_pk_mul_f32 v[22:23], v[22:23], v[162:163] op_sel_hi:[1,0]
	v_pk_mul_f32 v[20:21], v[20:21], v[162:163] op_sel_hi:[1,0]
	v_pk_mul_f32 v[18:19], v[18:19], v[162:163] op_sel_hi:[1,0]
	v_pk_add_f32 v[98:99], v[98:99], v[0:1] op_sel_hi:[1,0] neg_lo:[0,1] neg_hi:[0,1]
	v_pk_add_f32 v[52:53], v[52:53], v[0:1] op_sel_hi:[1,0] neg_lo:[0,1] neg_hi:[0,1]
	v_pk_add_f32 v[68:69], v[68:69], v[0:1] op_sel_hi:[1,0] neg_lo:[0,1] neg_hi:[0,1]
	v_pk_add_f32 v[84:85], v[84:85], v[0:1] op_sel_hi:[1,0] neg_lo:[0,1] neg_hi:[0,1]
	v_pk_add_f32 v[100:101], v[100:101], v[0:1] op_sel_hi:[1,0] neg_lo:[0,1] neg_hi:[0,1]
	v_pk_add_f32 v[54:55], v[54:55], v[0:1] op_sel_hi:[1,0] neg_lo:[0,1] neg_hi:[0,1]
	v_pk_add_f32 v[70:71], v[70:71], v[0:1] op_sel_hi:[1,0] neg_lo:[0,1] neg_hi:[0,1]
	v_pk_add_f32 v[86:87], v[86:87], v[0:1] op_sel_hi:[1,0] neg_lo:[0,1] neg_hi:[0,1]
	v_pk_add_f32 v[102:103], v[102:103], v[0:1] op_sel_hi:[1,0] neg_lo:[0,1] neg_hi:[0,1]
	v_pk_add_f32 v[56:57], v[56:57], v[0:1] op_sel_hi:[1,0] neg_lo:[0,1] neg_hi:[0,1]
	v_pk_add_f32 v[72:73], v[72:73], v[0:1] op_sel_hi:[1,0] neg_lo:[0,1] neg_hi:[0,1]
	v_pk_add_f32 v[88:89], v[88:89], v[0:1] op_sel_hi:[1,0] neg_lo:[0,1] neg_hi:[0,1]
	v_pk_add_f32 v[104:105], v[104:105], v[0:1] op_sel_hi:[1,0] neg_lo:[0,1] neg_hi:[0,1]
	v_pk_add_f32 v[58:59], v[58:59], v[0:1] op_sel_hi:[1,0] neg_lo:[0,1] neg_hi:[0,1]
	v_pk_add_f32 v[74:75], v[74:75], v[0:1] op_sel_hi:[1,0] neg_lo:[0,1] neg_hi:[0,1]
	v_pk_add_f32 v[90:91], v[90:91], v[0:1] op_sel_hi:[1,0] neg_lo:[0,1] neg_hi:[0,1]
	v_pk_add_f32 v[106:107], v[106:107], v[0:1] op_sel_hi:[1,0] neg_lo:[0,1] neg_hi:[0,1]
	v_pk_add_f32 v[60:61], v[60:61], v[0:1] op_sel_hi:[1,0] neg_lo:[0,1] neg_hi:[0,1]
	v_pk_add_f32 v[76:77], v[76:77], v[0:1] op_sel_hi:[1,0] neg_lo:[0,1] neg_hi:[0,1]
	v_pk_add_f32 v[92:93], v[92:93], v[0:1] op_sel_hi:[1,0] neg_lo:[0,1] neg_hi:[0,1]
	v_pk_add_f32 v[108:109], v[108:109], v[0:1] op_sel_hi:[1,0] neg_lo:[0,1] neg_hi:[0,1]
	v_pk_add_f32 v[62:63], v[62:63], v[0:1] op_sel_hi:[1,0] neg_lo:[0,1] neg_hi:[0,1]
	v_pk_add_f32 v[78:79], v[78:79], v[0:1] op_sel_hi:[1,0] neg_lo:[0,1] neg_hi:[0,1]
	v_pk_add_f32 v[94:95], v[94:95], v[0:1] op_sel_hi:[1,0] neg_lo:[0,1] neg_hi:[0,1]
	v_pk_add_f32 v[110:111], v[110:111], v[0:1] op_sel_hi:[1,0] neg_lo:[0,1] neg_hi:[0,1]
	v_pk_add_f32 v[64:65], v[64:65], v[0:1] op_sel_hi:[1,0] neg_lo:[0,1] neg_hi:[0,1]
	v_pk_add_f32 v[80:81], v[80:81], v[0:1] op_sel_hi:[1,0] neg_lo:[0,1] neg_hi:[0,1]
	v_pk_add_f32 v[96:97], v[96:97], v[0:1] op_sel_hi:[1,0] neg_lo:[0,1] neg_hi:[0,1]
	v_pk_add_f32 v[112:113], v[112:113], v[0:1] op_sel_hi:[1,0] neg_lo:[0,1] neg_hi:[0,1]
	v_sub_f32_e32 v49, v49, v0
	v_sub_f32_e32 v48, v48, v0
	v_sub_f32_e32 v47, v47, v0
	v_sub_f32_e32 v46, v46, v0
	v_sub_f32_e32 v45, v45, v0
	v_sub_f32_e32 v44, v44, v0
	v_sub_f32_e32 v43, v43, v0
	v_sub_f32_e32 v42, v42, v0
	v_sub_f32_e32 v41, v41, v0
	v_sub_f32_e32 v40, v40, v0
	v_sub_f32_e32 v39, v39, v0
	v_sub_f32_e32 v38, v38, v0
	v_sub_f32_e32 v37, v37, v0
	v_sub_f32_e32 v36, v36, v0
	v_sub_f32_e32 v35, v35, v0
	v_sub_f32_e32 v34, v34, v0
	v_mul_f32_e32 v246, v246, v162
	v_mul_f32_e32 v202, v202, v162
	v_mul_f32_e32 v203, v203, v162
	v_mul_f32_e32 v204, v204, v162
	v_mul_f32_e32 v205, v205, v162
	v_mul_f32_e32 v206, v206, v162
	v_mul_f32_e32 v207, v207, v162
	v_mul_f32_e32 v208, v208, v162
	v_mul_f32_e32 v211, v211, v162
	v_mul_f32_e32 v212, v212, v162
	v_mul_f32_e32 v213, v213, v162
	v_mul_f32_e32 v214, v214, v162
	v_mul_f32_e32 v215, v215, v162
	v_mul_f32_e32 v216, v216, v162
.LBB0_302:
	s_addk_i32 s7, 0x2400
	v_add3_u32 v0, v198, s7, v200
	v_cvt_pk_bf16_f32 v166, v246, v202
	v_cvt_pk_bf16_f32 v167, v203, v204
	v_cvt_pk_bf16_f32 v168, v205, v206
	v_cvt_pk_bf16_f32 v169, v207, v208
	v_exp_f32_e32 v209, v58
	v_exp_f32_e32 v210, v59
	s_waitcnt lgkmcnt(4)
	v_mfma_f32_32x32x16_bf16 v[18:33], v[238:241], v[166:169], v[18:33]
	ds_read_b128 v[238:241], v247 offset:57920
	s_waitcnt lgkmcnt(4)
	v_mfma_f32_32x32x16_bf16 v[2:17], v[242:245], v[166:169], v[2:17]
	ds_read_b128 v[242:245], v247 offset:53344
	v_cvt_pk_bf16_f32 v162, v209, v210
	v_cvt_pk_bf16_f32 v163, v211, v212
	v_cvt_pk_bf16_f32 v164, v213, v214
	v_cvt_pk_bf16_f32 v165, v215, v216
	v_exp_f32_e32 v217, v66
	v_exp_f32_e32 v218, v67
	s_waitcnt lgkmcnt(4)
	v_mfma_f32_32x32x16_bf16 v[18:33], v[226:229], v[162:165], v[18:33]
	ds_read_b128 v[226:229], v247 offset:57952
	v_exp_f32_e32 v219, v68
	v_exp_f32_e32 v220, v69
	v_exp_f32_e32 v221, v70
	v_exp_f32_e32 v222, v71
	v_exp_f32_e32 v223, v72
	v_exp_f32_e32 v224, v73
	v_cvt_pk_bf16_f32 v70, v217, v218
	s_waitcnt lgkmcnt(4)
	v_mfma_f32_32x32x16_bf16 v[2:17], v[230:233], v[162:165], v[2:17]
	ds_read_b128 v[230:233], v0 offset:53248
	v_cvt_pk_bf16_f32 v71, v219, v220
	v_cvt_pk_bf16_f32 v72, v221, v222
	v_cvt_pk_bf16_f32 v73, v223, v224
	v_exp_f32_e32 v74, v74
	v_exp_f32_e32 v75, v75
	v_exp_f32_e32 v76, v76
	s_waitcnt lgkmcnt(4)
	v_mfma_f32_32x32x16_bf16 v[18:33], v[234:237], v[70:73], v[18:33]
	ds_read_b128 v[234:237], v0 offset:57856
	v_exp_f32_e32 v77, v77
	v_exp_f32_e32 v78, v78
	v_exp_f32_e32 v79, v79
	v_exp_f32_e32 v80, v80
	v_exp_f32_e32 v81, v81
	v_cvt_pk_bf16_f32 v66, v74, v75
	s_waitcnt lgkmcnt(4)
	v_mfma_f32_32x32x16_bf16 v[2:17], v[238:241], v[70:73], v[2:17]
	ds_read_b128 v[238:241], v0 offset:53280
	v_cvt_pk_bf16_f32 v67, v76, v77
	v_cvt_pk_bf16_f32 v68, v78, v79
	v_cvt_pk_bf16_f32 v69, v80, v81
	v_exp_f32_e32 v82, v82
	v_exp_f32_e32 v83, v83
	s_waitcnt lgkmcnt(4)
	v_mfma_f32_32x32x16_bf16 v[18:33], v[242:245], v[66:69], v[18:33]
	ds_read_b128 v[242:245], v0 offset:57888
	v_exp_f32_e32 v84, v84
	v_exp_f32_e32 v85, v85
	v_exp_f32_e32 v86, v86
	v_exp_f32_e32 v87, v87
	v_exp_f32_e32 v88, v88
	v_exp_f32_e32 v89, v89
	s_waitcnt lgkmcnt(4)
	v_mfma_f32_32x32x16_bf16 v[2:17], v[226:229], v[66:69], v[2:17]
	ds_read_b128 v[226:229], v0 offset:53312
	v_cvt_pk_bf16_f32 v62, v82, v83
	v_cvt_pk_bf16_f32 v63, v84, v85
	v_cvt_pk_bf16_f32 v64, v86, v87
	v_cvt_pk_bf16_f32 v65, v88, v89
	v_exp_f32_e32 v90, v90
	v_exp_f32_e32 v91, v91
	s_waitcnt lgkmcnt(4)
	v_mfma_f32_32x32x16_bf16 v[18:33], v[230:233], v[62:65], v[18:33]
	ds_read_b128 v[230:233], v0 offset:57920
	v_exp_f32_e32 v92, v92
	v_exp_f32_e32 v93, v93
	v_exp_f32_e32 v94, v94
	v_exp_f32_e32 v95, v95
	v_exp_f32_e32 v96, v96
	v_exp_f32_e32 v97, v97
	s_waitcnt lgkmcnt(4)
	v_mfma_f32_32x32x16_bf16 v[2:17], v[234:237], v[62:65], v[2:17]
	ds_read_b128 v[234:237], v0 offset:53344
	v_cvt_pk_bf16_f32 v58, v90, v91
	v_cvt_pk_bf16_f32 v59, v92, v93
	v_cvt_pk_bf16_f32 v60, v94, v95
	v_cvt_pk_bf16_f32 v61, v96, v97
	v_exp_f32_e32 v98, v98
	v_exp_f32_e32 v99, v99
	s_waitcnt lgkmcnt(4)
	v_mfma_f32_32x32x16_bf16 v[18:33], v[238:241], v[58:61], v[18:33]
	ds_read_b128 v[238:241], v0 offset:57952
	v_exp_f32_e32 v100, v100
	v_exp_f32_e32 v101, v101
	v_exp_f32_e32 v102, v102
	v_exp_f32_e32 v103, v103
	v_exp_f32_e32 v104, v104
	v_exp_f32_e32 v105, v105
	v_cvt_pk_bf16_f32 v54, v98, v99
	s_waitcnt lgkmcnt(4)
	v_mfma_f32_32x32x16_bf16 v[2:17], v[242:245], v[58:61], v[2:17]
	v_cvt_pk_bf16_f32 v55, v100, v101
	v_cvt_pk_bf16_f32 v56, v102, v103
	v_cvt_pk_bf16_f32 v57, v104, v105
	v_exp_f32_e32 v106, v106
	v_exp_f32_e32 v107, v107
	v_exp_f32_e32 v108, v108
	s_waitcnt lgkmcnt(3)
	v_mfma_f32_32x32x16_bf16 v[18:33], v[226:229], v[54:57], v[18:33]
	v_exp_f32_e32 v109, v109
	v_exp_f32_e32 v110, v110
	v_exp_f32_e32 v111, v111
	v_exp_f32_e32 v112, v112
	v_exp_f32_e32 v113, v113
	v_cvt_pk_bf16_f32 v50, v106, v107
	s_waitcnt lgkmcnt(2)
	v_mfma_f32_32x32x16_bf16 v[2:17], v[230:233], v[54:57], v[2:17]
	v_cvt_pk_bf16_f32 v51, v108, v109
	v_cvt_pk_bf16_f32 v52, v110, v111
	v_cvt_pk_bf16_f32 v53, v112, v113
	s_add_i32 s15, s14, -2
	s_cmp_ge_u32 s15, s23
	s_waitcnt lgkmcnt(1)
	v_mfma_f32_32x32x16_bf16 v[18:33], v[234:237], v[50:53], v[18:33]
	s_waitcnt lgkmcnt(0)
	v_mfma_f32_32x32x16_bf16 v[2:17], v[238:241], v[50:53], v[2:17]
	s_branch .LBB0_299

.Lgqa_B_ls_end:
	v_add_f32_e32 v165, v111, v165
	v_add_f32_e32 v242, v112, v242
	v_add_f32_e32 v165, v113, v165
	v_add_f32_e32 v242, v82, v242
	v_add_f32_e32 v165, v83, v165
	v_add_f32_e32 v242, v84, v242
	s_waitcnt lgkmcnt(6)
	v_mfma_f32_32x32x16_bf16 v[50:65], v[226:229], v[126:129], v[50:65]
	ds_read_b128 v[226:229], v0 offset:64
	v_add_f32_e32 v165, v85, v165
	v_add_f32_e32 v242, v86, v242
	v_add_f32_e32 v165, v87, v165
	v_add_f32_e32 v242, v88, v242
	v_add_f32_e32 v165, v89, v165
	v_add_f32_e32 v242, v90, v242
	s_waitcnt lgkmcnt(6)
	v_mfma_f32_32x32x16_bf16 v[66:81], v[230:233], v[114:117], v[34:49]
	ds_read_b128 v[230:233], v0 offset:96
	v_add_f32_e32 v165, v91, v165
	v_add_f32_e32 v242, v92, v242
	v_add_f32_e32 v165, v93, v165
	v_add_f32_e32 v242, v94, v242
	v_add_f32_e32 v165, v95, v165
	s_waitcnt lgkmcnt(6)
	v_mfma_f32_32x32x16_bf16 v[66:81], v[234:237], v[118:121], v[66:81]
	ds_read_b128 v[234:237], v0 offset:13824
	v_add_f32_e32 v242, v96, v242
	v_add_f32_e32 v165, v97, v165
	v_add_f32_e32 v242, v166, v242
	v_add_f32_e32 v165, v167, v165
	v_add_f32_e32 v242, v168, v242
	s_waitcnt lgkmcnt(6)
	v_mfma_f32_32x32x16_bf16 v[66:81], v[238:241], v[122:125], v[66:81]
	ds_read_b128 v[238:241], v0 offset:13856
	v_add_f32_e32 v165, v169, v165
	v_add_f32_e32 v242, v170, v242
	v_add_f32_e32 v165, v171, v165
	v_add_f32_e32 v242, v172, v242
	v_add_f32_e32 v165, v173, v165
	v_max3_f32 v146, v50, v51, v52
	v_max3_f32 v146, v146, v53, v54
	s_waitcnt lgkmcnt(6)
	v_mfma_f32_32x32x16_bf16 v[66:81], v[214:217], v[126:129], v[66:81]
	ds_read_b128 v[214:217], v0 offset:13888
	v_add_f32_e32 v242, v174, v242
	v_add_f32_e32 v165, v175, v165
	v_add_f32_e32 v242, v176, v242
	v_add_f32_e32 v165, v177, v165
	v_add_f32_e32 v242, v178, v242
	v_max3_f32 v146, v146, v55, v56
	v_max3_f32 v146, v146, v57, v58
	s_waitcnt lgkmcnt(6)
	v_mfma_f32_32x32x16_bf16 v[98:113], v[218:221], v[114:117], v[34:49]
	ds_read_b128 v[218:221], v0 offset:13920
	v_add_f32_e32 v165, v179, v165
	v_add_f32_e32 v242, v191, v242
	v_add_f32_e32 v165, v192, v165
	v_add_f32_e32 v242, v193, v242
	v_max3_f32 v146, v146, v59, v60
	v_max3_f32 v146, v146, v61, v62
	s_waitcnt lgkmcnt(6)
	v_mfma_f32_32x32x16_bf16 v[98:113], v[222:225], v[118:121], v[98:113]
	ds_read_b128 v[206:209], v0 offset:36864
	v_add_f32_e32 v165, v194, v165
	v_add_f32_e32 v242, v195, v242
	v_add_f32_e32 v165, v196, v165
	v_add_f32_e32 v242, v197, v242
	v_max3_f32 v146, v146, v63, v64
	v_max3_f32 v146, v146, v65, v65
	s_waitcnt lgkmcnt(6)
	v_mfma_f32_32x32x16_bf16 v[98:113], v[226:229], v[122:125], v[98:113]
	ds_read_b128 v[210:213], v0 offset:41472
	v_add_f32_e32 v165, v198, v165
	v_add_f32_e32 v242, v199, v242
	v_add_f32_e32 v165, v200, v165
	v_add_f32_e32 v242, v201, v242
	v_max3_f32 v146, v146, v66, v67
	v_max3_f32 v146, v146, v68, v69
	s_waitcnt lgkmcnt(6)
	v_mfma_f32_32x32x16_bf16 v[98:113], v[230:233], v[126:129], v[98:113]
	ds_read_b128 v[222:225], v0 offset:36896
	v_add_f32_e32 v165, v202, v165
	v_add_f32_e32 v242, v203, v242
	v_add_f32_e32 v165, v204, v165
	v_add_f32_e32 v165, v242, v165
	v_max3_f32 v146, v146, v70, v71
	v_max3_f32 v146, v146, v72, v73
	s_waitcnt lgkmcnt(6)
	v_mfma_f32_32x32x16_bf16 v[82:97], v[234:237], v[114:117], v[34:49]
	ds_read_b128 v[226:229], v0 offset:41504
	v_max3_f32 v146, v146, v74, v75
	v_max3_f32 v146, v146, v76, v77
	v_exp_f32_e32 v196, v53
	v_exp_f32_e32 v197, v54
	v_exp_f32_e32 v198, v55
	s_waitcnt lgkmcnt(6)
	v_mfma_f32_32x32x16_bf16 v[82:97], v[238:241], v[118:121], v[82:97]
	ds_read_b128 v[230:233], v0 offset:36928
	v_max3_f32 v146, v146, v78, v79
	v_max3_f32 v146, v146, v80, v81
	v_exp_f32_e32 v199, v56
	v_exp_f32_e32 v200, v57
	v_exp_f32_e32 v204, v61
	s_waitcnt lgkmcnt(6)
	v_mfma_f32_32x32x16_bf16 v[82:97], v[214:217], v[122:125], v[82:97]
	ds_read_b128 v[234:237], v0 offset:41536
	s_waitcnt lgkmcnt(6)
	v_mfma_f32_32x32x16_bf16 v[82:97], v[218:221], v[126:129], v[82:97]
	v_max3_f32 v146, v146, v98, v99
	v_max3_f32 v146, v146, v100, v101
	v_max3_f32 v146, v146, v102, v103
	v_max3_f32 v146, v146, v104, v105
	v_max3_f32 v146, v146, v106, v107
	v_max3_f32 v146, v146, v108, v109
	v_max3_f32 v146, v146, v110, v111
	v_max3_f32 v146, v146, v112, v113
	s_nop 3
	v_max3_f32 v146, v146, v82, v83
	v_max3_f32 v146, v146, v84, v85
	v_max3_f32 v146, v146, v86, v87
	v_max3_f32 v146, v146, v88, v89
	v_max3_f32 v146, v146, v90, v91
	v_max3_f32 v146, v146, v92, v93
	v_max3_f32 v146, v146, v94, v95
	v_max3_f32 v146, v146, v96, v97
	v_mov_b32_e32 v147, v146
	s_nop 1
	v_permlane32_swap_b32_e32 v146, v147
	v_max_f32_e32 v146, v146, v147
	v_cmp_lt_f32_e32 vcc, s50, v146
	s_cbranch_vccz .LBB0_350
	v_max_f32_e32 v146, v146, v146
	v_max_f32_e32 v146, 0, v146
	v_exp_f32_e64 v148, -v146
	v_pk_add_f32 v[98:99], v[98:99], v[146:147] op_sel_hi:[1,0] neg_lo:[0,1] neg_hi:[0,1]
	v_pk_add_f32 v[66:67], v[66:67], v[146:147] op_sel_hi:[1,0] neg_lo:[0,1] neg_hi:[0,1]
	v_pk_add_f32 v[50:51], v[50:51], v[146:147] op_sel_hi:[1,0] neg_lo:[0,1] neg_hi:[0,1]
	v_mul_f32_e32 v165, v165, v148
	v_pk_mul_f32 v[16:17], v[16:17], v[148:149] op_sel_hi:[1,0]
	v_pk_mul_f32 v[14:15], v[14:15], v[148:149] op_sel_hi:[1,0]
	v_pk_mul_f32 v[12:13], v[12:13], v[148:149] op_sel_hi:[1,0]
	v_pk_mul_f32 v[10:11], v[10:11], v[148:149] op_sel_hi:[1,0]
	v_pk_mul_f32 v[8:9], v[8:9], v[148:149] op_sel_hi:[1,0]
	v_pk_mul_f32 v[6:7], v[6:7], v[148:149] op_sel_hi:[1,0]
	v_pk_mul_f32 v[4:5], v[4:5], v[148:149] op_sel_hi:[1,0]
	v_pk_mul_f32 v[2:3], v[2:3], v[148:149] op_sel_hi:[1,0]
	v_pk_mul_f32 v[32:33], v[32:33], v[148:149] op_sel_hi:[1,0]
	v_pk_mul_f32 v[30:31], v[30:31], v[148:149] op_sel_hi:[1,0]
	v_pk_mul_f32 v[28:29], v[28:29], v[148:149] op_sel_hi:[1,0]
	v_pk_mul_f32 v[26:27], v[26:27], v[148:149] op_sel_hi:[1,0]
	v_pk_mul_f32 v[24:25], v[24:25], v[148:149] op_sel_hi:[1,0]
	v_pk_mul_f32 v[22:23], v[22:23], v[148:149] op_sel_hi:[1,0]
	v_pk_mul_f32 v[20:21], v[20:21], v[148:149] op_sel_hi:[1,0]
	v_pk_mul_f32 v[18:19], v[18:19], v[148:149] op_sel_hi:[1,0]
	v_pk_add_f32 v[82:83], v[82:83], v[146:147] op_sel_hi:[1,0] neg_lo:[0,1] neg_hi:[0,1]
	v_pk_add_f32 v[100:101], v[100:101], v[146:147] op_sel_hi:[1,0] neg_lo:[0,1] neg_hi:[0,1]
	v_pk_add_f32 v[68:69], v[68:69], v[146:147] op_sel_hi:[1,0] neg_lo:[0,1] neg_hi:[0,1]
	v_pk_add_f32 v[52:53], v[52:53], v[146:147] op_sel_hi:[1,0] neg_lo:[0,1] neg_hi:[0,1]
	v_pk_add_f32 v[84:85], v[84:85], v[146:147] op_sel_hi:[1,0] neg_lo:[0,1] neg_hi:[0,1]
	v_pk_add_f32 v[102:103], v[102:103], v[146:147] op_sel_hi:[1,0] neg_lo:[0,1] neg_hi:[0,1]
	v_pk_add_f32 v[70:71], v[70:71], v[146:147] op_sel_hi:[1,0] neg_lo:[0,1] neg_hi:[0,1]
	v_pk_add_f32 v[54:55], v[54:55], v[146:147] op_sel_hi:[1,0] neg_lo:[0,1] neg_hi:[0,1]
	v_pk_add_f32 v[86:87], v[86:87], v[146:147] op_sel_hi:[1,0] neg_lo:[0,1] neg_hi:[0,1]
	v_pk_add_f32 v[104:105], v[104:105], v[146:147] op_sel_hi:[1,0] neg_lo:[0,1] neg_hi:[0,1]
	v_pk_add_f32 v[72:73], v[72:73], v[146:147] op_sel_hi:[1,0] neg_lo:[0,1] neg_hi:[0,1]
	v_pk_add_f32 v[56:57], v[56:57], v[146:147] op_sel_hi:[1,0] neg_lo:[0,1] neg_hi:[0,1]
	v_pk_add_f32 v[88:89], v[88:89], v[146:147] op_sel_hi:[1,0] neg_lo:[0,1] neg_hi:[0,1]
	v_pk_add_f32 v[106:107], v[106:107], v[146:147] op_sel_hi:[1,0] neg_lo:[0,1] neg_hi:[0,1]
	v_pk_add_f32 v[74:75], v[74:75], v[146:147] op_sel_hi:[1,0] neg_lo:[0,1] neg_hi:[0,1]
	v_pk_add_f32 v[58:59], v[58:59], v[146:147] op_sel_hi:[1,0] neg_lo:[0,1] neg_hi:[0,1]
	v_pk_add_f32 v[90:91], v[90:91], v[146:147] op_sel_hi:[1,0] neg_lo:[0,1] neg_hi:[0,1]
	v_pk_add_f32 v[108:109], v[108:109], v[146:147] op_sel_hi:[1,0] neg_lo:[0,1] neg_hi:[0,1]
	v_pk_add_f32 v[76:77], v[76:77], v[146:147] op_sel_hi:[1,0] neg_lo:[0,1] neg_hi:[0,1]
	v_pk_add_f32 v[60:61], v[60:61], v[146:147] op_sel_hi:[1,0] neg_lo:[0,1] neg_hi:[0,1]
	v_pk_add_f32 v[92:93], v[92:93], v[146:147] op_sel_hi:[1,0] neg_lo:[0,1] neg_hi:[0,1]
	v_pk_add_f32 v[110:111], v[110:111], v[146:147] op_sel_hi:[1,0] neg_lo:[0,1] neg_hi:[0,1]
	v_pk_add_f32 v[78:79], v[78:79], v[146:147] op_sel_hi:[1,0] neg_lo:[0,1] neg_hi:[0,1]
	v_pk_add_f32 v[62:63], v[62:63], v[146:147] op_sel_hi:[1,0] neg_lo:[0,1] neg_hi:[0,1]
	v_pk_add_f32 v[94:95], v[94:95], v[146:147] op_sel_hi:[1,0] neg_lo:[0,1] neg_hi:[0,1]
	v_pk_add_f32 v[112:113], v[112:113], v[146:147] op_sel_hi:[1,0] neg_lo:[0,1] neg_hi:[0,1]
	v_pk_add_f32 v[80:81], v[80:81], v[146:147] op_sel_hi:[1,0] neg_lo:[0,1] neg_hi:[0,1]
	v_pk_add_f32 v[64:65], v[64:65], v[146:147] op_sel_hi:[1,0] neg_lo:[0,1] neg_hi:[0,1]
	v_pk_add_f32 v[96:97], v[96:97], v[146:147] op_sel_hi:[1,0] neg_lo:[0,1] neg_hi:[0,1]
	v_sub_f32_e32 v49, v49, v146
	v_sub_f32_e32 v48, v48, v146
	v_sub_f32_e32 v47, v47, v146
	v_sub_f32_e32 v46, v46, v146
	v_sub_f32_e32 v45, v45, v146
	v_sub_f32_e32 v44, v44, v146
	v_sub_f32_e32 v43, v43, v146
	v_sub_f32_e32 v42, v42, v146
	v_sub_f32_e32 v41, v41, v146
	v_sub_f32_e32 v40, v40, v146
	v_sub_f32_e32 v39, v39, v146
	v_sub_f32_e32 v38, v38, v146
	v_sub_f32_e32 v37, v37, v146
	v_sub_f32_e32 v36, v36, v146
	v_sub_f32_e32 v35, v35, v146
	v_sub_f32_e32 v34, v34, v146
	v_mul_f32_e32 v196, v196, v148
	v_mul_f32_e32 v197, v197, v148
	v_mul_f32_e32 v198, v198, v148
	v_mul_f32_e32 v199, v199, v148
	v_mul_f32_e32 v200, v200, v148
	v_mul_f32_e32 v204, v204, v148
.LBB0_350:
	v_exp_f32_e32 v166, v98
	v_exp_f32_e32 v167, v99
	v_exp_f32_e32 v168, v100
	v_exp_f32_e32 v169, v101
	v_exp_f32_e32 v170, v102
	v_exp_f32_e32 v171, v103
	v_exp_f32_e32 v172, v104
	v_exp_f32_e32 v173, v105
	v_cvt_pk_bf16_f32 v146, v166, v167
	v_cvt_pk_bf16_f32 v147, v168, v169
	v_cvt_pk_bf16_f32 v148, v170, v171
	v_cvt_pk_bf16_f32 v149, v172, v173
	v_exp_f32_e32 v106, v106
	v_exp_f32_e32 v107, v107
	s_waitcnt lgkmcnt(5)
	v_mfma_f32_32x32x16_bf16 v[18:33], v[206:209], v[146:149], v[18:33]
	ds_read_b128 v[206:209], v0 offset:36960
	v_exp_f32_e32 v108, v108
	v_exp_f32_e32 v109, v109
	v_exp_f32_e32 v110, v110
	v_exp_f32_e32 v111, v111
	v_exp_f32_e32 v112, v112
	v_exp_f32_e32 v113, v113
	s_waitcnt lgkmcnt(5)
	v_mfma_f32_32x32x16_bf16 v[2:17], v[210:213], v[146:149], v[2:17]
	ds_read_b128 v[210:213], v0 offset:41568
	v_cvt_pk_bf16_f32 v102, v106, v107
	v_cvt_pk_bf16_f32 v103, v108, v109
	v_cvt_pk_bf16_f32 v104, v110, v111
	v_cvt_pk_bf16_f32 v105, v112, v113
	v_exp_f32_e32 v174, v66
	v_exp_f32_e32 v175, v67
	s_waitcnt lgkmcnt(5)
	v_mfma_f32_32x32x16_bf16 v[18:33], v[222:225], v[102:105], v[18:33]
	ds_read_b128 v[222:225], v0 offset:46080
	v_exp_f32_e32 v176, v68
	v_exp_f32_e32 v177, v69
	v_exp_f32_e32 v178, v70
	v_exp_f32_e32 v179, v71
	v_exp_f32_e32 v191, v72
	v_exp_f32_e32 v192, v73
	v_cvt_pk_bf16_f32 v98, v174, v175
	s_waitcnt lgkmcnt(5)
	v_mfma_f32_32x32x16_bf16 v[2:17], v[226:229], v[102:105], v[2:17]
	ds_read_b128 v[226:229], v0 offset:50688
	v_cvt_pk_bf16_f32 v99, v176, v177
	v_cvt_pk_bf16_f32 v100, v178, v179
	v_cvt_pk_bf16_f32 v101, v191, v192
	v_exp_f32_e32 v74, v74
	v_exp_f32_e32 v75, v75
	v_exp_f32_e32 v76, v76
	s_waitcnt lgkmcnt(5)
	v_mfma_f32_32x32x16_bf16 v[18:33], v[230:233], v[98:101], v[18:33]
	ds_read_b128 v[230:233], v0 offset:46112
	v_exp_f32_e32 v77, v77
	v_exp_f32_e32 v78, v78
	v_exp_f32_e32 v79, v79
	v_exp_f32_e32 v80, v80
	v_exp_f32_e32 v81, v81
	v_cvt_pk_bf16_f32 v70, v74, v75
	s_waitcnt lgkmcnt(5)
	v_mfma_f32_32x32x16_bf16 v[2:17], v[234:237], v[98:101], v[2:17]
	ds_read_b128 v[234:237], v0 offset:50720
	v_cvt_pk_bf16_f32 v71, v76, v77
	v_cvt_pk_bf16_f32 v72, v78, v79
	v_cvt_pk_bf16_f32 v73, v80, v81
	v_exp_f32_e32 v193, v50
	v_exp_f32_e32 v194, v51
	v_exp_f32_e32 v195, v52
	s_waitcnt lgkmcnt(5)
	v_mfma_f32_32x32x16_bf16 v[18:33], v[206:209], v[70:73], v[18:33]
	ds_read_b128 v[206:209], v0 offset:46144
	v_cvt_pk_bf16_f32 v66, v193, v194
	s_waitcnt lgkmcnt(5)
	v_mfma_f32_32x32x16_bf16 v[2:17], v[210:213], v[70:73], v[2:17]
	ds_read_b128 v[210:213], v0 offset:50752
	v_cvt_pk_bf16_f32 v67, v195, v196
	v_cvt_pk_bf16_f32 v68, v197, v198
	v_cvt_pk_bf16_f32 v69, v199, v200
	v_exp_f32_e32 v201, v58
	v_exp_f32_e32 v202, v59
	v_exp_f32_e32 v203, v60
	s_waitcnt lgkmcnt(5)
	v_mfma_f32_32x32x16_bf16 v[18:33], v[222:225], v[66:69], v[18:33]
	ds_read_b128 v[222:225], v0 offset:46176
	v_exp_f32_e32 v62, v62
	v_exp_f32_e32 v63, v63
	v_exp_f32_e32 v64, v64
	v_exp_f32_e32 v65, v65
	v_cvt_pk_bf16_f32 v58, v201, v202
	s_waitcnt lgkmcnt(5)
	v_mfma_f32_32x32x16_bf16 v[2:17], v[226:229], v[66:69], v[2:17]
	ds_read_b128 v[226:229], v0 offset:50784
	v_cvt_pk_bf16_f32 v59, v203, v204
	v_cvt_pk_bf16_f32 v60, v62, v63
	v_cvt_pk_bf16_f32 v61, v64, v65
	v_exp_f32_e32 v82, v82
	v_exp_f32_e32 v83, v83
	v_exp_f32_e32 v84, v84
	s_waitcnt lgkmcnt(5)
	v_mfma_f32_32x32x16_bf16 v[18:33], v[230:233], v[58:61], v[18:33]
	v_exp_f32_e32 v85, v85
	v_exp_f32_e32 v86, v86
	v_exp_f32_e32 v87, v87
	v_exp_f32_e32 v88, v88
	v_exp_f32_e32 v89, v89
	v_cvt_pk_bf16_f32 v54, v82, v83
	s_waitcnt lgkmcnt(4)
	v_mfma_f32_32x32x16_bf16 v[2:17], v[234:237], v[58:61], v[2:17]
	v_cvt_pk_bf16_f32 v55, v84, v85
	v_cvt_pk_bf16_f32 v56, v86, v87
	v_cvt_pk_bf16_f32 v57, v88, v89
	v_exp_f32_e32 v90, v90
	v_exp_f32_e32 v91, v91
	v_exp_f32_e32 v92, v92
	s_waitcnt lgkmcnt(3)
	v_mfma_f32_32x32x16_bf16 v[18:33], v[206:209], v[54:57], v[18:33]
	v_exp_f32_e32 v93, v93
	v_exp_f32_e32 v94, v94
	v_exp_f32_e32 v95, v95
	v_exp_f32_e32 v96, v96
	v_exp_f32_e32 v97, v97
	v_cvt_pk_bf16_f32 v50, v90, v91
	s_waitcnt lgkmcnt(2)
	v_mfma_f32_32x32x16_bf16 v[2:17], v[210:213], v[54:57], v[2:17]
	v_cvt_pk_bf16_f32 v51, v92, v93
	v_cvt_pk_bf16_f32 v52, v94, v95
	v_cvt_pk_bf16_f32 v53, v96, v97
	s_add_i32 s13, s12, -2
	s_cmp_ge_u32 s13, s23
	s_waitcnt lgkmcnt(1)
	v_mfma_f32_32x32x16_bf16 v[18:33], v[222:225], v[50:53], v[18:33]
	s_waitcnt lgkmcnt(0)
	v_mfma_f32_32x32x16_bf16 v[2:17], v[226:229], v[50:53], v[2:17]
	s_branch .LBB0_347
